# selected stream: short per-stage DMA issue path when no tile clamping is needed (per-lane offsets for tiles 1..3); on top of v34
# baseline (speedup 1.0000x reference)
; #define LAS __attribute__((address_space(3)))
; __device__ __forceinline__ int launder_v(int x) { asm volatile("" : "+v"(x)); return x; }
; __device__ __forceinline__ int launder_s(int x) { x = __builtin_amdgcn_readfirstlane(x); asm volatile("" : "+s"(x)); return x; }
; template <int STG, class F>
; __device__ __forceinline__ void stream_tiles(Ctx& C, const TileSrc& src, int tile0, int ntiles, LAS unsigned char* bufs, F&& compute) {
;     ...
;     const int nst = (ntiles + STG - 1) / STG, tlast = tile0 + ntiles - 1;
;     v4u rk[STG], rv[STG];
;     { const int tidl = launder_v(C.tid);
; #pragma unroll
;       for (int h = 0; h < STG; ++h) { const int t = tile0 + h; tile_fetch(src, 64 * (t < tlast ? t : tlast), tidl, rk[h], rv[h]); }
; #pragma unroll
;       for (int h = 0; h < STG; ++h) tile_store(bufs + h * 16384, tidl, rk[h], rv[h]); }
;     __syncthreads();
; __device__ __forceinline__ void nsa_block_task(Ctx& C, int task, bf16* ONSA_OUT) {
;     ...
; #pragma unroll
;         for (int cg = 0; cg < 2; ++cg)
; #pragma unroll
;             for (int c = 0; c < 4; ++c) oc[cg][c] = o[cg][c] * g_c[cg];
;     }
;     WAVE_SYNC();
;     {
; #pragma unroll 1
;         for (int q = 0; q < 8; ++q) {
;             if (qb < 16) { if (lane < 8) SELM[q * 8 + lane] = (lane == 0) ? ((1u << (qb + 1)) - 1u) : 0u; }
;             else select_blocks(SC + q * 256, SELM + q * 8, qb - 2, qb, qb - 1, lane);
;         }
;     }
;     WAVE_SYNC();
;     LAS unsigned* ANYM = (LAS unsigned*)(C.lds + 135168 + w * 64);
;     { const int la = launder_v(lane); if (la < 16) { const int cgx = la >> 3, w8 = la & 7; ANYM[la] = SELM[(4 * cgx + 0) * 8 + w8] | SELM[(4 * cgx + 1) * 8 + w8] | SELM[(4 * cgx + 2) * 8 + w8] | SELM[(4 * cgx + 3) * 8 + w8]; } }
;     WAVE_SYNC();
;     f4* STASH = WSP(f4, WS_STASH) + (size_t)(C.bid * NWAVES + w) * 512;
; #pragma unroll
;     for (int cg = 0; cg < 2; ++cg)
; #pragma unroll
;         for (int c = 0; c < 4; ++c) STASH[(cg * 4 + c) * 64 + lane] = oc[cg][c];
;     __syncthreads();
;     {
;         AttnAcc a[2]; attn_init(a[0]); attn_init(a[1]);
;         const int kvs = launder_s(kvh);
;         const TileSrc src{WSP(bf16, WS_KS) + (size_t)kvs * RP * 64, WSP(bf16, WS_VST) + (size_t)kvs * 64 * RP, RP};
;         int cw = -1; unsigned aw0 = 0u, aw1 = 0u;
;         stream_tiles<4>(C, src, 0, qb, bufs, [&](const LAS unsigned char* buf, int j) {
.LBB0_1206:
	s_or_b64 exec, exec, s[16:17]
	v_pk_mul_f32 v[32:33], v[186:187], v[32:33] op_sel_hi:[0,1]
	v_pk_mul_f32 v[34:35], v[186:187], v[34:35] op_sel_hi:[0,1]
	s_mov_b32 s3, s97
	v_pk_mul_f32 v[48:49], v[186:187], v[48:49] op_sel_hi:[0,1]
	v_pk_mul_f32 v[50:51], v[186:187], v[50:51] op_sel_hi:[0,1]
	v_pk_mul_f32 v[44:45], v[186:187], v[44:45] op_sel_hi:[0,1]
	v_pk_mul_f32 v[46:47], v[186:187], v[46:47] op_sel_hi:[0,1]
	v_pk_mul_f32 v[36:37], v[182:183], v[36:37] op_sel_hi:[0,1]
	v_pk_mul_f32 v[38:39], v[182:183], v[38:39] op_sel_hi:[0,1]
	v_pk_mul_f32 v[40:41], v[182:183], v[40:41] op_sel_hi:[0,1]
	v_pk_mul_f32 v[42:43], v[182:183], v[42:43] op_sel_hi:[0,1]
	v_pk_mul_f32 v[28:29], v[186:187], v[28:29] op_sel_hi:[0,1]
	v_pk_mul_f32 v[30:31], v[186:187], v[30:31] op_sel_hi:[0,1]
	v_pk_mul_f32 v[20:21], v[182:183], v[20:21] op_sel_hi:[0,1]
	v_pk_mul_f32 v[22:23], v[182:183], v[22:23] op_sel_hi:[0,1]
	v_pk_mul_f32 v[24:25], v[182:183], v[24:25] op_sel_hi:[0,1]
	v_pk_mul_f32 v[26:27], v[182:183], v[26:27] op_sel_hi:[0,1]
	s_waitcnt lgkmcnt(0)
	v_mov_b64_e32 v[176:177], v[32:33]
	v_mov_b64_e32 v[178:179], v[34:35]
	v_mov_b64_e32 v[180:181], v[48:49]
	v_mov_b64_e32 v[204:205], v[50:51]
	v_mov_b64_e32 v[206:207], v[28:29]
	v_mov_b64_e32 v[208:209], v[30:31]
	v_mov_b64_e32 v[234:235], v[44:45]
	v_mov_b64_e32 v[236:237], v[46:47]
	v_mov_b64_e32 v[238:239], v[20:21]
	v_mov_b64_e32 v[240:241], v[22:23]
	v_mov_b64_e32 v[242:243], v[36:37]
	v_mov_b64_e32 v[244:245], v[38:39]
	v_mov_b64_e32 v[246:247], v[24:25]
	v_mov_b64_e32 v[248:249], v[26:27]
	v_mov_b64_e32 v[250:251], v[40:41]
	v_mov_b64_e32 v[252:253], v[42:43]
	s_waitcnt lgkmcnt(0)
	s_barrier
	s_mul_hi_i32 s17, s3, 0x208000
	s_mul_i32 s3, s3, 0x208000
	s_add_u32 s18, s79, s3
	s_addc_u32 s19, s80, s17
	s_add_u32 s16, s81, s3
	s_addc_u32 s17, s82, s17
	s_cmp_eq_u32 s94, 0
	s_mov_b32 s26, 0
	s_cbranch_scc1 .LBB0_1229
	v_mov_b32_e32 v36, v189
	s_add_i32 s3, s94, 3
	v_ashrrev_i32_e32 v20, 3, v36
	v_lshlrev_b32_e32 v28, 4, v36
	v_and_b32_e32 v0, 0x70, v28
	v_ashrrev_i32_e32 v21, 31, v20
	v_mov_b64_e32 v[22:23], s[16:17]
	v_lshl_add_u64 v[2:3], s[18:19], 0, v[0:1]
	v_mad_i64_i32 v[22:23], s[20:21], v20, s92, v[22:23]
	v_lshlrev_b64 v[24:25], 7, v[20:21]
	s_cmp_eq_u32 s0, 0
	v_lshl_add_u64 v[24:25], v[2:3], 0, v[24:25]
	s_cselect_b32 s20, 0, 64
	v_lshl_add_u64 v[22:23], v[22:23], 0, v[0:1]
	v_add_u32_e32 v24, s20, v20
	v_ashrrev_i32_e32 v25, 31, v24
	v_lshlrev_b64 v[24:25], 7, v[24:25]
	v_lshl_add_u64 v[24:25], v[2:3], 0, v[24:25]
	s_lshl_b32 s50, s20, 1
	s_min_u32 s20, s0, 2
	v_lshl_add_u64 v[26:27], v[22:23], 0, s[50:51]
	v_lshl_add_u32 v24, s20, 6, v20
	v_ashrrev_i32_e32 v25, 31, v24
	v_lshlrev_b64 v[24:25], 7, v[24:25]
	v_lshl_add_u64 v[24:25], v[2:3], 0, v[24:25]
	s_lshl_b32 s50, s20, 7
	s_min_u32 s20, s0, 3
	v_lshl_add_u64 v[26:27], v[22:23], 0, s[50:51]
	v_lshl_add_u32 v24, s20, 6, v20
	v_ashrrev_i32_e32 v25, 31, v24
	v_lshlrev_b64 v[24:25], 7, v[24:25]
	v_lshl_add_u64 v[2:3], v[2:3], 0, v[24:25]
	s_lshl_b32 s50, s20, 7
	v_lshl_add_u64 v[22:23], v[22:23], 0, s[50:51]
	v_lshrrev_b32_e32 v233, 3, v189
	v_and_b32_e32 v254, 7, v189
	v_bfe_u32 v174, v233, 1, 3
	v_xor_b32_e32 v254, v254, v174
	v_lshlrev_b32_e32 v254, 4, v254
	v_mul_lo_u32 v198, v233, s92
	v_add_u32_e32 v198, v198, v254
	v_and_b32_e32 v174, 32, v233
	v_bfe_u32 v175, v233, 2, 2
	v_lshl_or_b32 v174, v175, 3, v174
	v_bfe_u32 v175, v233, 4, 1
	v_lshl_or_b32 v174, v175, 2, v174
	v_and_or_b32 v174, v233, 3, v174
	v_lshl_add_u32 v185, v174, 7, v254
	v_add_u32_e32 v56, 0x2000, v185
	v_add_u32_e32 v57, 0x80, v198
	v_add_u32_e32 v58, 0x4000, v185
	v_add_u32_e32 v59, 0x100, v198
	v_add_u32_e32 v60, 0x6000, v185
	v_add_u32_e32 v61, 0x180, v198
	v_readfirstlane_b32 s44, v189
	s_lshl_b32 s44, s44, 4
	s_mov_b32 s28, 0
	s_mov_b32 s3, 0
	s_add_i32 s45, s3, s44
	s_min_i32 s24, s28, s0
	s_add_i32 m0, s45, 0x0
	s_lshl_b32 s98, s24, 13
	s_add_u32 s98, s18, s98
	s_addc_u32 s99, s19, 0
	global_load_lds_dwordx4 v185, s[98:99]
	s_add_i32 m0, s45, 0x2000
	s_lshl_b32 s100, s24, 7
	s_add_u32 s100, s16, s100
	s_addc_u32 s101, s17, 0
	global_load_lds_dwordx4 v198, s[100:101]
	s_add_i32 s24, s28, 1
	s_min_i32 s24, s24, s0
	s_add_i32 m0, s45, 0x4000
	s_lshl_b32 s98, s24, 13
	s_add_u32 s98, s18, s98
	s_addc_u32 s99, s19, 0
	global_load_lds_dwordx4 v185, s[98:99]
	s_add_i32 m0, s45, 0x6000
	s_lshl_b32 s100, s24, 7
	s_add_u32 s100, s16, s100
	s_addc_u32 s101, s17, 0
	global_load_lds_dwordx4 v198, s[100:101]
	s_add_i32 s24, s28, 2
	s_min_i32 s24, s24, s0
	s_add_i32 m0, s45, 0x8000
	s_lshl_b32 s98, s24, 13
	s_add_u32 s98, s18, s98
	s_addc_u32 s99, s19, 0
	global_load_lds_dwordx4 v185, s[98:99]
	s_add_i32 m0, s45, 0xa000
	s_lshl_b32 s100, s24, 7
	s_add_u32 s100, s16, s100
	s_addc_u32 s101, s17, 0
	global_load_lds_dwordx4 v198, s[100:101]
	s_add_i32 s24, s28, 3
	s_min_i32 s24, s24, s0
	s_add_i32 m0, s45, 0xc000
	s_lshl_b32 s98, s24, 13
	s_add_u32 s98, s18, s98
	s_addc_u32 s99, s19, 0
	global_load_lds_dwordx4 v185, s[98:99]
	s_add_i32 m0, s45, 0xe000
	s_lshl_b32 s100, s24, 7
	s_add_u32 s100, s16, s100
	s_addc_u32 s101, s17, 0
	global_load_lds_dwordx4 v198, s[100:101]
	s_add_i32 s3, s94, 3
	v_lshlrev_b32_e32 v0, 2, v20
	v_lshrrev_b32_e32 v21, 1, v20
	v_mov_b32_e32 v2, v1
	v_mov_b32_e32 v3, v1
	v_and_b32_e32 v22, 35, v20
	v_lshlrev_b32_e32 v20, 7, v20
	v_bitop3_b32 v23, v28, s91, v36 bitop3:0x48
	v_and_b32_e32 v24, 16, v0
	v_and_b32_e32 v21, 12, v21
	v_add3_u32 v37, 0, v20, v23
	v_mov_b32_e32 v0, v1
	v_or3_b32 v38, v24, v22, v21
	v_mov_b64_e32 v[22:23], v[2:3]
	v_mov_b64_e32 v[26:27], v[2:3]
	v_mov_b64_e32 v[30:31], v[2:3]
	v_mov_b64_e32 v[34:35], v[2:3]
	v_mov_b64_e32 v[42:43], v[2:3]
	v_mov_b64_e32 v[46:47], v[2:3]
	v_mov_b64_e32 v[50:51], v[2:3]
	v_mov_b64_e32 v[54:55], v[2:3]
	v_mov_b64_e32 v[20:21], v[0:1]
	v_mov_b64_e32 v[24:25], v[0:1]
	v_mov_b64_e32 v[28:29], v[0:1]
	v_mov_b64_e32 v[32:33], v[0:1]
	v_mov_b64_e32 v[40:41], v[0:1]
	v_mov_b64_e32 v[44:45], v[0:1]
	v_mov_b64_e32 v[48:49], v[0:1]
	v_mov_b64_e32 v[52:53], v[0:1]
	v_lshrrev_b32_e32 v2, 1, v38
	v_xor_b32_e32 v2, v2, v36
	v_lshlrev_b32_e32 v2, 4, v2
	v_lshlrev_b32_e32 v0, 7, v38
	v_and_b32_e32 v2, 0x70, v2
	s_mov_b32 s27, 0
	v_mov_b32_e32 v169, 0xc4800000
	v_mov_b32_e32 v168, 0
	s_mov_b32 s22, -1
	s_mov_b32 s49, -1
	s_mov_b32 s28, 0
	s_mov_b32 s31, 0
	s_mov_b32 s30, 0
	s_lshr_b32 s29, s3, 2
	v_add3_u32 v0, 0, v0, v2
	v_mov_b32_e32 v36, 0
	v_mov_b32_e32 v170, 0xc4800000
	s_mov_b32 s23, 0
	v_ashrrev_i32_e32 v226, 4, v190
	v_lshrrev_b32_e32 v225, 1, v190
	v_bitop3_b32 v233, v225, v226, 7 bitop3:0x6c
	v_lshlrev_b32_e32 v254, 7, v190
	v_add_u32_e32 v226, 4, v226
	v_lshlrev_b32_e32 v233, 4, v233
	v_and_b32_e32 v254, 0x780, v254
	v_bitop3_b32 v226, v226, v225, 7 bitop3:0x78
	v_lshlrev_b32_e32 v226, 4, v226
	v_add_u32_e32 v225, v254, v233
	v_add_u32_e32 v226, v254, v226
	s_waitcnt vmcnt(0) lgkmcnt(0)
	s_waitcnt lgkmcnt(0)
	s_barrier
; __device__ __forceinline__ int launder_v(int x) { asm volatile("" : "+v"(x)); return x; }
; template <int STG, class F>
; __device__ __forceinline__ void stream_tiles(Ctx& C, const TileSrc& src, int tile0, int ntiles, LAS unsigned char* bufs, F&& compute) {
;     ...
;     for (int st = 0; st < nst; ++st) {
;         const int tidl = launder_v(C.tid);
;         const bool more = st + 1 < nst;
;         if (more) {
; #pragma unroll
;             for (int h = 0; h < STG; ++h) { const int t = tile0 + STG * (st + 1) + h; tile_fetch(src, 64 * (t < tlast ? t : tlast), tidl, rk[h], rv[h]); } }
.LBB0_1208:
	s_add_i32 s34, s23, 1
	v_mov_b32_e32 v37, v189
	s_cmp_lt_u32 s34, s29
	s_cselect_b64 s[20:21], -1, 0
	v_ashrrev_i32_e32 v38, 3, v37
	v_lshlrev_b32_e32 v39, 4, v37
	s_cmp_ge_u32 s34, s29
	s_cbranch_scc1 .LBB0_1210
	s_lshl_b32 s3, s34, 2
	s_lshl_b32 s25, s34, 16
	s_and_b32 s25, s25, 0x10000
	s_add_i32 s45, s25, s44
	s_add_i32 s24, s3, 3
	s_cmp_gt_i32 s24, s0
	s_cbranch_scc1 .Lseld_clamped
	s_lshl_b32 s98, s3, 13
	s_add_u32 s98, s18, s98
	s_addc_u32 s99, s19, 0
	s_add_i32 m0, s45, 0x0
	s_lshl_b32 s100, s3, 7
	global_load_lds_dwordx4 v185, s[98:99]
	s_add_i32 m0, s45, 0x2000
	s_add_u32 s100, s16, s100
	s_addc_u32 s101, s17, 0
	global_load_lds_dwordx4 v198, s[100:101]
	s_add_i32 m0, s45, 0x4000
	s_nop 0
	global_load_lds_dwordx4 v56, s[98:99]
	s_add_i32 m0, s45, 0x6000
	s_nop 0
	global_load_lds_dwordx4 v57, s[100:101]
	s_add_i32 m0, s45, 0x8000
	s_nop 0
	global_load_lds_dwordx4 v58, s[98:99]
	s_add_i32 m0, s45, 0xa000
	s_nop 0
	global_load_lds_dwordx4 v59, s[100:101]
	s_add_i32 m0, s45, 0xc000
	s_nop 0
	global_load_lds_dwordx4 v60, s[98:99]
	s_add_i32 m0, s45, 0xe000
	s_nop 0
	global_load_lds_dwordx4 v61, s[100:101]
	s_branch .LBB0_1210
.Lseld_clamped:
	s_min_i32 s24, s3, s0
	s_add_i32 m0, s45, 0x0
	s_lshl_b32 s98, s24, 13
	s_add_u32 s98, s18, s98
	s_addc_u32 s99, s19, 0
	global_load_lds_dwordx4 v185, s[98:99]
	s_add_i32 m0, s45, 0x2000
	s_lshl_b32 s100, s24, 7
	s_add_u32 s100, s16, s100
	s_addc_u32 s101, s17, 0
	global_load_lds_dwordx4 v198, s[100:101]
	s_add_i32 s24, s3, 1
	s_min_i32 s24, s24, s0
	s_add_i32 m0, s45, 0x4000
	s_lshl_b32 s98, s24, 13
	s_add_u32 s98, s18, s98
	s_addc_u32 s99, s19, 0
	global_load_lds_dwordx4 v185, s[98:99]
	s_add_i32 m0, s45, 0x6000
	s_lshl_b32 s100, s24, 7
	s_add_u32 s100, s16, s100
	s_addc_u32 s101, s17, 0
	global_load_lds_dwordx4 v198, s[100:101]
	s_add_i32 s24, s3, 2
	s_min_i32 s24, s24, s0
	s_add_i32 m0, s45, 0x8000
	s_lshl_b32 s98, s24, 13
	s_add_u32 s98, s18, s98
	s_addc_u32 s99, s19, 0
	global_load_lds_dwordx4 v185, s[98:99]
	s_add_i32 m0, s45, 0xa000
	s_lshl_b32 s100, s24, 7
	s_add_u32 s100, s16, s100
	s_addc_u32 s101, s17, 0
	global_load_lds_dwordx4 v198, s[100:101]
	s_add_i32 s24, s3, 3
	s_min_i32 s24, s24, s0
	s_add_i32 m0, s45, 0xc000
	s_lshl_b32 s98, s24, 13
	s_add_u32 s98, s18, s98
	s_addc_u32 s99, s19, 0
	global_load_lds_dwordx4 v185, s[98:99]
	s_add_i32 m0, s45, 0xe000
	s_lshl_b32 s100, s24, 7
	s_add_u32 s100, s16, s100
	s_addc_u32 s101, s17, 0
	global_load_lds_dwordx4 v198, s[100:101]
